# hoisted first QK K-fragment LDS reads above the K/V staging ds_writes in both diff-attention loops (uses free VGPRs 244-253)
# baseline (speedup 1.0000x reference)
; #define SBAR() __builtin_amdgcn_sched_barrier(0)
; #define PVF(...) do { if constexpr (!MLA || ATT_PIPE_MLA) pv_pipe(__VA_ARGS__); else pv_d0(__VA_ARGS__); } while (0)
; #define SWRITE(b) do { *(bf16x8*)(V_lds + (b) * SHM_V + vst0) = vs0; *(bf16x8*)(V_lds + (b) * SHM_V + vst1) = vs1; \
;     if constexpr (MLA) { *(bf16x8*)(KN_lds + (b) * SHM_KN + KSWZ(sr, sc * 2)) = kn0; *(bf16x8*)(KN_lds + (b) * SHM_KN + KSWZ(32 + sr, sc * 2)) = kn1; } \
;     *(bf16x8*)(KR_lds + (b) * SHM_KR + KSWZ2(kr_r, kr_c * 2)) = kr0; } while (0)
; #define SWAIT() asm volatile("s_waitcnt vmcnt(0)" ::: "memory")
; __device__ __forceinline__ void qkt_pre(f32x16& p0, f32x16& p1, const char* Kr, const bf16x8* qr, const f32x16& negm, int r32, int hi) {
; #pragma unroll
;   for (int d0 = 0; d0 < 4; ++d0) { const int cb = (d0 * 16 + hi * 8) * 2;
;     const bf16x8 b0 = *reinterpret_cast<const bf16x8*>(Kr + KSWZ2(r32, cb));
;     const bf16x8 b1 = *reinterpret_cast<const bf16x8*>(Kr + KSWZ2(32 + r32, cb));
;     if (d0 == 0) { p0 = __builtin_amdgcn_mfma_f32_32x32x16_bf16(b0, qr[0], negm, 0, 0, 0); p1 = __builtin_amdgcn_mfma_f32_32x32x16_bf16(b1, qr[0], negm, 0, 0, 0); }
;     else { p0 = __builtin_amdgcn_mfma_f32_32x32x16_bf16(b0, qr[d0], p0, 0, 0, 0); p1 = __builtin_amdgcn_mfma_f32_32x32x16_bf16(b1, qr[d0], p1, 0, 0, 0); } }
; template <bool MLA> ...
;     ...
;       SWAIT(); SWRITE(bW);
;       SBAR(); qkt_pre(pB0, pB1, KR_lds + bK * SHM_KR, qr, negm, r32, hi);
;       finishSM(pA0, pA1, alA, l_reg, pa0, pa1, pa2, pa3); SBAR();
;       SLOAD((j + 2) * KVBLK); SBAR();
;       PVF(o, vb0 + bV * SHM_V, pa0, pa1, pa2, pa3); partialSM_pre<false>(pB0, pB1, Mref, negm, alB);
.LBB0_756:
	s_mov_b32 s11, s35
	s_mov_b32 s35, s10
	s_lshl_b32 s10, s10, 14
	s_add_i32 s10, s10, 0
	s_lshl_b32 s98, s36, 13
	v_add_u32_e32 v253, s98, v204
	ds_read_b128 v[244:247], v253 offset:53248
	ds_read_b128 v[98:101], v253 offset:49152
	s_waitcnt vmcnt(0)
	v_add_u32_e32 v252, s10, v196
	s_lshl_b32 s24, s35, 13
	s_waitcnt vmcnt(2)
	ds_write_b128 v252, v[148:151]
	v_add_u32_e32 v252, s10, v197
	s_sub_i32 s24, s10, s24
	s_waitcnt vmcnt(1)
	ds_write_b128 v252, v[152:155]
	v_add_u32_e32 v252, s24, v199
	s_waitcnt vmcnt(0)
	ds_write_b128 v252, v[156:159] offset:49152
	s_lshl_b32 s10, s36, 13
	s_add_i32 s10, s10, 0
	v_add_u32_e32 v152, s10, v205
	v_exp_f32_e32 v156, v90
	v_exp_f32_e32 v157, v91
	v_exp_f32_e32 v158, v92
	s_waitcnt lgkmcnt(3)
	v_mfma_f32_32x32x16_bf16 v[114:129], v[98:101], v[144:147], v[66:81]
	v_exp_f32_e32 v159, v93
	v_exp_f32_e32 v166, v94
	v_exp_f32_e32 v167, v95
	v_exp_f32_e32 v180, v96
	v_exp_f32_e32 v97, v97
	v_cvt_pk_bf16_f32 v94, v156, v157
	v_cvt_pk_bf16_f32 v95, v158, v159
	v_mfma_f32_32x32x16_bf16 v[98:113], v[244:247], v[144:147], v[66:81]
	ds_read_b128 v[148:151], v152 offset:53248
	ds_read_b128 v[152:155], v152 offset:49152
	v_cvt_pk_bf16_f32 v96, v166, v167
	s_nop 1
	v_permlane32_swap_b32_e32 v94, v96
	s_waitcnt lgkmcnt(1)
	v_mfma_f32_32x32x16_bf16 v[98:113], v[148:151], v[140:143], v[98:113]
	s_waitcnt lgkmcnt(0)
	v_mfma_f32_32x32x16_bf16 v[114:129], v[152:155], v[140:143], v[114:129]
	v_add_u32_e32 v152, s10, v206
	ds_read_b128 v[148:151], v152 offset:53248
	ds_read_b128 v[152:155], v152 offset:49152
	s_waitcnt lgkmcnt(1)
	v_mfma_f32_32x32x16_bf16 v[98:113], v[148:151], v[136:139], v[98:113]
	s_waitcnt lgkmcnt(0)
	v_mfma_f32_32x32x16_bf16 v[114:129], v[152:155], v[136:139], v[114:129]
	v_add_u32_e32 v152, s10, v207
	ds_read_b128 v[148:151], v152 offset:53248
	ds_read_b128 v[152:155], v152 offset:49152
	s_waitcnt lgkmcnt(1)
	v_mfma_f32_32x32x16_bf16 v[98:113], v[148:151], v[132:135], v[98:113]
	v_exp_f32_e32 v148, v82
	v_add_f32_e32 v82, 0, v217
	v_add_f32_e32 v82, v218, v82
	v_add_f32_e32 v82, v219, v82
	v_add_f32_e32 v82, v220, v82
	v_add_f32_e32 v82, v221, v82
	v_add_f32_e32 v82, v222, v82
	v_add_f32_e32 v82, v223, v82
	v_add_f32_e32 v82, v224, v82
	v_add_f32_e32 v82, v181, v82
	v_add_f32_e32 v82, v182, v82
	v_add_f32_e32 v82, v183, v82
	v_add_f32_e32 v82, v184, v82
	v_add_f32_e32 v82, v185, v82
	v_exp_f32_e32 v149, v83
	v_add_f32_e32 v82, v214, v82
	v_exp_f32_e32 v150, v84
	v_add_f32_e32 v82, v215, v82
	v_exp_f32_e32 v151, v85
	v_add_f32_e32 v82, v216, v82
	s_waitcnt lgkmcnt(0)
	v_mfma_f32_32x32x16_bf16 v[114:129], v[152:155], v[132:135], v[114:129]
	v_exp_f32_e32 v152, v86
	v_add_f32_e32 v82, v148, v82
	v_exp_f32_e32 v153, v87
	v_add_f32_e32 v82, v149, v82
	v_exp_f32_e32 v154, v88
	v_add_f32_e32 v82, v150, v82
	v_exp_f32_e32 v155, v89
	v_add_f32_e32 v82, v151, v82
	v_add_f32_e32 v82, v152, v82
	v_add_f32_e32 v82, v153, v82
	v_add_f32_e32 v82, v154, v82
	v_add_f32_e32 v82, v155, v82
	v_add_f32_e32 v82, v156, v82
	v_add_f32_e32 v82, v157, v82
	v_add_f32_e32 v82, v158, v82
	v_add_f32_e32 v82, v159, v82
	v_add_f32_e32 v82, v166, v82
	v_add_f32_e32 v82, v167, v82
	v_add_f32_e32 v82, v180, v82
	v_add_f32_e32 v209, v97, v82
	v_mov_b32_e32 v210, v209
	v_cvt_pk_bf16_f32 v82, v217, v218
	v_cvt_pk_bf16_f32 v84, v221, v222
	v_permlane32_swap_b32_e32 v209, v210
	v_cvt_pk_bf16_f32 v83, v219, v220
	v_cvt_pk_bf16_f32 v85, v223, v224
	v_permlane32_swap_b32_e32 v82, v84
	v_cvt_pk_bf16_f32 v86, v181, v182
	v_cvt_pk_bf16_f32 v87, v183, v184
	v_cvt_pk_bf16_f32 v88, v185, v214
	v_cvt_pk_bf16_f32 v89, v215, v216
	v_cvt_pk_bf16_f32 v90, v148, v149
	v_cvt_pk_bf16_f32 v91, v150, v151
	v_cvt_pk_bf16_f32 v92, v152, v153
	v_cvt_pk_bf16_f32 v93, v154, v155
	v_cvt_pk_bf16_f32 v97, v180, v97
	v_permlane32_swap_b32_e32 v83, v85
	v_permlane32_swap_b32_e32 v86, v88
	v_permlane32_swap_b32_e32 v87, v89
	v_permlane32_swap_b32_e32 v90, v92
	v_permlane32_swap_b32_e32 v91, v93
	v_permlane32_swap_b32_e32 v95, v97
	v_lshl_add_u64 v[184:185], s[8:9], 0, v[174:175]
	v_add_co_u32_e32 v148, vcc, s62, v184
	v_lshl_add_u64 v[182:183], s[8:9], 0, v[176:177]
	s_nop 0
	v_addc_co_u32_e32 v149, vcc, 0, v185, vcc
	v_add_co_u32_e32 v152, vcc, s62, v182
	v_lshl_add_u64 v[180:181], s[8:9], 0, v[178:179]
	s_nop 0
	v_addc_co_u32_e32 v153, vcc, 0, v183, vcc
	v_add_co_u32_e32 v156, vcc, s63, v180
	global_load_dwordx4 v[148:151], v[148:149], off
	s_nop 0
	global_load_dwordx4 v[152:155], v[152:153], off
	v_addc_co_u32_e32 v157, vcc, 0, v181, vcc
	global_load_dwordx4 v[156:159], v[156:157], off offset:2176
	v_lshl_add_u32 v166, s11, 14, v173
	ds_read_b64_tr_b16 v[212:213], v166 offset:0
	ds_read_b64_tr_b16 v[214:215], v166 offset:0x800
	ds_read_b64_tr_b16 v[216:217], v166 offset:0x1000
	ds_read_b64_tr_b16 v[218:219], v166 offset:0x1800
	ds_read_b64_tr_b16 v[220:221], v166 offset:0x2000
	ds_read_b64_tr_b16 v[222:223], v166 offset:0x2800
	ds_read_b64_tr_b16 v[224:225], v166 offset:0x3000
	ds_read_b64_tr_b16 v[226:227], v166 offset:0x3800
	s_waitcnt lgkmcnt(0)
; #define SBAR() __builtin_amdgcn_sched_barrier(0)
; #define PV_READ(S, D0) do { S##0 = tr_read<v_rd_off(D0, 0, 0)>(vb); S##1 = tr_read<v_rd_off(D0, 0, 1)>(vb); S##2 = tr_read<v_rd_off(D0, 1, 0)>(vb); S##3 = tr_read<v_rd_off(D0, 1, 1)>(vb); \
;     S##4 = tr_read<v_rd_off(D0, 2, 0)>(vb); S##5 = tr_read<v_rd_off(D0, 2, 1)>(vb); S##6 = tr_read<v_rd_off(D0, 3, 0)>(vb); S##7 = tr_read<v_rd_off(D0, 3, 1)>(vb); } while (0)
; #define PV_MMA(OD, S) do { OD = __builtin_amdgcn_mfma_f32_32x32x16_bf16(pa0, PV_PK(S##0, S##1), OD, 0, 0, 0); OD = __builtin_amdgcn_mfma_f32_32x32x16_bf16(pa1, PV_PK(S##2, S##3), OD, 0, 0, 0); \
;     OD = __builtin_amdgcn_mfma_f32_32x32x16_bf16(pa2, PV_PK(S##4, S##5), OD, 0, 0, 0); OD = __builtin_amdgcn_mfma_f32_32x32x16_bf16(pa3, PV_PK(S##6, S##7), OD, 0, 0, 0); } while (0)
; #define PV_WAIT() do { asm volatile("s_waitcnt lgkmcnt(0)" ::: "memory"); SBAR(); } while (0)
; template <bool FIRST> __device__ __forceinline__ void partialSM_pre(f32x16& p0, f32x16& p1, float& M, f32x16& negm, float& alpha) {
;   constexpr float THRL = THR * 1.4426950408889634f;
;   float pmax = p0[0];
; #pragma unroll
;   for (int r = 1; r < 16; ++r) pmax = fmaxf(pmax, p0[r]);
; #pragma unroll
;   for (int r = 0; r < 16; ++r) pmax = fmaxf(pmax, p1[r]);
;   { auto rr = __builtin_amdgcn_permlane32_swap(__float_as_uint(pmax), __float_as_uint(pmax), false, false);
;     pmax = fmaxf(__uint_as_float(rr[0]), __uint_as_float(rr[1])); }
;   if (!FIRST && __builtin_expect(__all(pmax <= THRL), 1)) { alpha = 1.f; }
; __device__ __forceinline__ void pv_pipe(f32x16* o, int vb, bf16x8 pa0, bf16x8 pa1, bf16x8 pa2, bf16x8 pa3) {
;   s16x4 a0, a1, a2, a3, a4, a5, a6, a7, b0, b1, b2, b3, b4, b5, b6, b7;
;   PV_READ(a, 0); PV_WAIT();
;   PV_READ(b, 1); SBAR(); PV_MMA(o[0], a); PV_WAIT();
;   PV_READ(a, 2); SBAR(); PV_MMA(o[1], b); PV_WAIT();
;   PV_READ(b, 3); SBAR(); PV_MMA(o[2], a); PV_WAIT();
;   PV_MMA(o[3], b);
; }
	ds_read_b64_tr_b16 v[228:229], v166 offset:0x200
	ds_read_b64_tr_b16 v[230:231], v166 offset:0xa00
	ds_read_b64_tr_b16 v[232:233], v166 offset:0x1200
	ds_read_b64_tr_b16 v[234:235], v166 offset:0x1a00
	ds_read_b64_tr_b16 v[236:237], v166 offset:0x2200
	ds_read_b64_tr_b16 v[238:239], v166 offset:0x2a00
	ds_read_b64_tr_b16 v[240:241], v166 offset:0x3200
	ds_read_b64_tr_b16 v[242:243], v166 offset:0x3a00
	s_nop 0
	v_mfma_f32_32x32x16_bf16 v[2:17], v[82:85], v[212:215], v[2:17]
	s_waitcnt lgkmcnt(0)
	v_mfma_f32_32x32x16_bf16 v[2:17], v[86:89], v[216:219], v[2:17]
	v_mfma_f32_32x32x16_bf16 v[2:17], v[90:93], v[220:223], v[2:17]
	v_mfma_f32_32x32x16_bf16 v[2:17], v[94:97], v[224:227], v[2:17]
	ds_read_b64_tr_b16 v[212:213], v166 offset:0x400
	ds_read_b64_tr_b16 v[214:215], v166 offset:0xc00
	ds_read_b64_tr_b16 v[216:217], v166 offset:0x1400
	ds_read_b64_tr_b16 v[218:219], v166 offset:0x1c00
	ds_read_b64_tr_b16 v[220:221], v166 offset:0x2400
	ds_read_b64_tr_b16 v[222:223], v166 offset:0x2c00
	ds_read_b64_tr_b16 v[224:225], v166 offset:0x3400
	ds_read_b64_tr_b16 v[226:227], v166 offset:0x3c00
	v_mfma_f32_32x32x16_bf16 v[50:65], v[82:85], v[228:231], v[50:65]
	s_waitcnt lgkmcnt(0)
	v_mfma_f32_32x32x16_bf16 v[50:65], v[86:89], v[232:235], v[50:65]
	v_mfma_f32_32x32x16_bf16 v[50:65], v[90:93], v[236:239], v[50:65]
	v_mfma_f32_32x32x16_bf16 v[50:65], v[94:97], v[240:243], v[50:65]
	ds_read_b64_tr_b16 v[228:229], v166 offset:0x600
	ds_read_b64_tr_b16 v[230:231], v166 offset:0xe00
	ds_read_b64_tr_b16 v[232:233], v166 offset:0x1600
	ds_read_b64_tr_b16 v[234:235], v166 offset:0x1e00
	ds_read_b64_tr_b16 v[236:237], v166 offset:0x2600
	ds_read_b64_tr_b16 v[238:239], v166 offset:0x2e00
	ds_read_b64_tr_b16 v[240:241], v166 offset:0x3600
	ds_read_b64_tr_b16 v[242:243], v166 offset:0x3e00
	v_mfma_f32_32x32x16_bf16 v[34:49], v[82:85], v[212:215], v[34:49]
	s_waitcnt lgkmcnt(0)
	v_mfma_f32_32x32x16_bf16 v[34:49], v[86:89], v[216:219], v[34:49]
	v_mfma_f32_32x32x16_bf16 v[34:49], v[90:93], v[220:223], v[34:49]
	v_mfma_f32_32x32x16_bf16 v[34:49], v[94:97], v[224:227], v[34:49]
	v_mfma_f32_32x32x16_bf16 v[18:33], v[82:85], v[228:231], v[18:33]
	v_max_f32_e32 v82, v115, v115
	v_max_f32_e32 v83, v114, v114
	v_max_f32_e32 v82, v83, v82
	v_max3_f32 v82, v82, v116, v117
	v_max3_f32 v82, v82, v118, v119
	v_max3_f32 v82, v82, v120, v121
	v_max3_f32 v82, v82, v122, v123
	v_mfma_f32_32x32x16_bf16 v[18:33], v[86:89], v[232:235], v[18:33]
	v_max3_f32 v82, v82, v124, v125
	v_max3_f32 v82, v82, v126, v127
	v_max3_f32 v82, v82, v128, v129
	v_max3_f32 v82, v82, v98, v99
	v_max3_f32 v82, v82, v100, v101
	v_max3_f32 v82, v82, v102, v103
	v_max3_f32 v82, v82, v104, v105
	v_mfma_f32_32x32x16_bf16 v[18:33], v[90:93], v[236:239], v[18:33]
	v_max3_f32 v82, v82, v106, v107
	v_max3_f32 v82, v82, v108, v109
	v_max3_f32 v82, v82, v110, v111
	v_max3_f32 v82, v82, v112, v113
	v_mov_b32_e32 v83, v82
	s_nop 1
	v_permlane32_swap_b32_e32 v82, v83
	v_mfma_f32_32x32x16_bf16 v[18:33], v[94:97], v[240:243], v[18:33]
	v_max_f32_e32 v83, v83, v83
	v_max_f32_e32 v82, v82, v82
	v_max_f32_e32 v82, v82, v83
	v_cmp_ge_f32_e32 vcc, s12, v82
	s_cmp_eq_u64 vcc, exec
	s_cbranch_scc0 .LBB0_770
	v_mov_b32_e32 v211, 1.0
	v_cmp_gt_f32_e32 vcc, 1.0, v211
	s_cbranch_vccz .LBB0_761

; #define SBAR() __builtin_amdgcn_sched_barrier(0)
; #define SWRITE(b) do { *(bf16x8*)(V_lds + (b) * SHM_V + vst0) = vs0; *(bf16x8*)(V_lds + (b) * SHM_V + vst1) = vs1; \
;     if constexpr (MLA) { *(bf16x8*)(KN_lds + (b) * SHM_KN + KSWZ(sr, sc * 2)) = kn0; *(bf16x8*)(KN_lds + (b) * SHM_KN + KSWZ(32 + sr, sc * 2)) = kn1; } \
;     *(bf16x8*)(KR_lds + (b) * SHM_KR + KSWZ2(kr_r, kr_c * 2)) = kr0; } while (0)
; #define SWAIT() asm volatile("s_waitcnt vmcnt(0)" ::: "memory")
; __device__ __forceinline__ void qkt_pre(f32x16& p0, f32x16& p1, const char* Kr, const bf16x8* qr, const f32x16& negm, int r32, int hi) {
; #pragma unroll
;   for (int d0 = 0; d0 < 4; ++d0) { const int cb = (d0 * 16 + hi * 8) * 2;
;     const bf16x8 b0 = *reinterpret_cast<const bf16x8*>(Kr + KSWZ2(r32, cb));
;     const bf16x8 b1 = *reinterpret_cast<const bf16x8*>(Kr + KSWZ2(32 + r32, cb));
;     if (d0 == 0) { p0 = __builtin_amdgcn_mfma_f32_32x32x16_bf16(b0, qr[0], negm, 0, 0, 0); p1 = __builtin_amdgcn_mfma_f32_32x32x16_bf16(b1, qr[0], negm, 0, 0, 0); }
;     else { p0 = __builtin_amdgcn_mfma_f32_32x32x16_bf16(b0, qr[d0], p0, 0, 0, 0); p1 = __builtin_amdgcn_mfma_f32_32x32x16_bf16(b1, qr[d0], p1, 0, 0, 0); } }
; template <bool MLA> ...
;     ...
;       SWAIT(); SWRITE(bW);
;       SBAR(); qkt_pre(pA0, pA1, KR_lds + bK * SHM_KR, qr, negm, r32, hi);
;       finishSM(pB0, pB1, alB, l_reg, pa0, pa1, pa2, pa3); SBAR();
;       if (j + 3 < NT) SLOAD((j + 3) * KVBLK); SBAR();
.LBB0_761:
	s_add_i32 s10, s35, 1
	s_cmp_lg_u32 s35, 2
	s_cselect_b32 s37, s10, 0
	s_lshl_b32 s10, s37, 14
	s_add_i32 s10, s10, 0
	s_barrier
	v_add_u32_e32 v253, s24, v204
	ds_read_b128 v[212:215], v253 offset:53248
	ds_read_b128 v[82:85], v253 offset:49152
	s_waitcnt vmcnt(0)
	v_add_u32_e32 v252, s10, v196
	s_waitcnt vmcnt(2)
	ds_write_b128 v252, v[148:151]
	v_add_u32_e32 v252, s10, v197
	s_waitcnt vmcnt(1)
	ds_write_b128 v252, v[152:155]
	v_lshl_add_u32 v252, s37, 13, v200
	v_exp_f32_e32 v166, v114
	v_exp_f32_e32 v167, v115
	v_exp_f32_e32 v220, v116
	v_exp_f32_e32 v221, v117
	v_exp_f32_e32 v222, v118
	v_exp_f32_e32 v223, v119
	v_exp_f32_e32 v224, v120
	v_exp_f32_e32 v225, v121
	v_exp_f32_e32 v226, v122
	v_exp_f32_e32 v227, v123
	v_exp_f32_e32 v228, v124
	v_exp_f32_e32 v229, v125
	v_exp_f32_e32 v230, v126
	v_exp_f32_e32 v231, v127
	v_exp_f32_e32 v232, v128
	v_exp_f32_e32 v233, v129
	s_waitcnt vmcnt(0)
	ds_write_b128 v252, v[156:159] offset:49152
	v_add_u32_e32 v216, s24, v205
	v_exp_f32_e32 v234, v104
	v_exp_f32_e32 v235, v105
	v_exp_f32_e32 v236, v106
	s_waitcnt lgkmcnt(3)
	v_mfma_f32_32x32x16_bf16 v[114:129], v[82:85], v[144:147], v[66:81]
	v_exp_f32_e32 v237, v107
	v_exp_f32_e32 v238, v108
	v_exp_f32_e32 v239, v109
	v_exp_f32_e32 v240, v110
	v_exp_f32_e32 v241, v111
	v_exp_f32_e32 v242, v112
	v_exp_f32_e32 v113, v113
	v_mfma_f32_32x32x16_bf16 v[82:97], v[212:215], v[144:147], v[66:81]
	ds_read_b128 v[212:215], v216 offset:53248
	ds_read_b128 v[216:219], v216 offset:49152
	v_cvt_pk_bf16_f32 v104, v230, v231
	v_cvt_pk_bf16_f32 v105, v232, v233
	v_cvt_pk_bf16_f32 v109, v234, v235
	v_cvt_pk_bf16_f32 v110, v236, v237
	v_cvt_pk_bf16_f32 v111, v238, v239
	v_cvt_pk_bf16_f32 v112, v240, v241
	s_waitcnt lgkmcnt(1)
	v_mfma_f32_32x32x16_bf16 v[82:97], v[212:215], v[140:143], v[82:97]
	v_permlane32_swap_b32_e32 v110, v112
	s_waitcnt lgkmcnt(0)
	v_mfma_f32_32x32x16_bf16 v[114:129], v[216:219], v[140:143], v[114:129]
	v_add_u32_e32 v216, s24, v206
	ds_read_b128 v[212:215], v216 offset:53248
	ds_read_b128 v[216:219], v216 offset:49152
	s_waitcnt lgkmcnt(1)
	v_mfma_f32_32x32x16_bf16 v[82:97], v[212:215], v[136:139], v[82:97]
	s_waitcnt lgkmcnt(0)
	v_mfma_f32_32x32x16_bf16 v[114:129], v[216:219], v[136:139], v[114:129]
	v_add_u32_e32 v216, s24, v207
	ds_read_b128 v[212:215], v216 offset:53248
	ds_read_b128 v[216:219], v216 offset:49152
	s_waitcnt lgkmcnt(1)
	v_mfma_f32_32x32x16_bf16 v[82:97], v[212:215], v[132:135], v[82:97]
	v_exp_f32_e32 v214, v98
	v_add_f32_e32 v98, 0, v166
	v_add_f32_e32 v98, v167, v98
	v_add_f32_e32 v98, v220, v98
	v_add_f32_e32 v98, v221, v98
	v_add_f32_e32 v98, v222, v98
	v_add_f32_e32 v98, v223, v98
	v_add_f32_e32 v98, v224, v98
	v_add_f32_e32 v98, v225, v98
	v_add_f32_e32 v98, v226, v98
	v_add_f32_e32 v98, v227, v98
	v_add_f32_e32 v98, v228, v98
	v_add_f32_e32 v98, v229, v98
	v_add_f32_e32 v98, v230, v98
	v_exp_f32_e32 v215, v99
	v_add_f32_e32 v98, v231, v98
	s_waitcnt lgkmcnt(0)
	v_mfma_f32_32x32x16_bf16 v[114:129], v[216:219], v[132:135], v[114:129]
	v_exp_f32_e32 v216, v100
	v_add_f32_e32 v98, v232, v98
	v_exp_f32_e32 v217, v101
	v_add_f32_e32 v98, v233, v98
	v_exp_f32_e32 v218, v102
	v_add_f32_e32 v98, v214, v98
	v_exp_f32_e32 v219, v103
	v_add_f32_e32 v98, v215, v98
	v_add_f32_e32 v98, v216, v98
	v_add_f32_e32 v98, v217, v98
	v_add_f32_e32 v98, v218, v98
	v_add_f32_e32 v98, v219, v98
	v_add_f32_e32 v98, v234, v98
	v_add_f32_e32 v98, v235, v98
	v_add_f32_e32 v98, v236, v98
	v_add_f32_e32 v98, v237, v98
	v_add_f32_e32 v98, v238, v98
	v_add_f32_e32 v98, v239, v98
	v_add_f32_e32 v98, v240, v98
	v_add_f32_e32 v98, v241, v98
	v_add_f32_e32 v98, v242, v98
	v_add_f32_e32 v212, v113, v98
	v_mov_b32_e32 v213, v212
	v_cvt_pk_bf16_f32 v98, v166, v167
	v_cvt_pk_bf16_f32 v99, v220, v221
	v_cvt_pk_bf16_f32 v100, v222, v223
	v_cvt_pk_bf16_f32 v101, v224, v225
	v_cvt_pk_bf16_f32 v102, v226, v227
	v_cvt_pk_bf16_f32 v103, v228, v229
	v_cvt_pk_bf16_f32 v106, v214, v215
	v_cvt_pk_bf16_f32 v107, v216, v217
	v_cvt_pk_bf16_f32 v108, v218, v219
	v_cvt_pk_bf16_f32 v113, v242, v113
	v_permlane32_swap_b32_e32 v212, v213
	v_permlane32_swap_b32_e32 v98, v100
	v_permlane32_swap_b32_e32 v99, v101
	v_permlane32_swap_b32_e32 v102, v104
	v_permlane32_swap_b32_e32 v103, v105
	v_permlane32_swap_b32_e32 v106, v108
	v_permlane32_swap_b32_e32 v107, v109
	v_permlane32_swap_b32_e32 v111, v113
	s_cmp_gt_u32 s34, 60
	s_cselect_b64 s[24:25], -1, 0
	s_and_b64 vcc, exec, s[24:25]
	s_cbranch_vccnz .LBB0_763
	v_add_co_u32_e32 v148, vcc, 0x19f81000, v184
	s_nop 1
	v_addc_co_u32_e32 v149, vcc, 0, v185, vcc
	v_add_co_u32_e32 v152, vcc, 0x19f81000, v182
	s_nop 1
	v_addc_co_u32_e32 v153, vcc, 0, v183, vcc
	v_add_co_u32_e32 v156, vcc, 0x19f80000, v180
	global_load_dwordx4 v[148:151], v[148:149], off
	s_nop 0
	global_load_dwordx4 v[152:155], v[152:153], off
	v_addc_co_u32_e32 v157, vcc, 0, v181, vcc
	global_load_dwordx4 v[156:159], v[156:157], off offset:2176

; #define SBAR() __builtin_amdgcn_sched_barrier(0)
; #define PVF(...) do { if constexpr (!MLA || ATT_PIPE_MLA) pv_pipe(__VA_ARGS__); else pv_d0(__VA_ARGS__); } while (0)
; #define SWRITE(b) do { *(bf16x8*)(V_lds + (b) * SHM_V + vst0) = vs0; *(bf16x8*)(V_lds + (b) * SHM_V + vst1) = vs1; \
;     if constexpr (MLA) { *(bf16x8*)(KN_lds + (b) * SHM_KN + KSWZ(sr, sc * 2)) = kn0; *(bf16x8*)(KN_lds + (b) * SHM_KN + KSWZ(32 + sr, sc * 2)) = kn1; } \
;     *(bf16x8*)(KR_lds + (b) * SHM_KR + KSWZ2(kr_r, kr_c * 2)) = kr0; } while (0)
; #define SWAIT() asm volatile("s_waitcnt vmcnt(0)" ::: "memory")
; __device__ __forceinline__ void qkt_pre(f32x16& p0, f32x16& p1, const char* Kr, const bf16x8* qr, const f32x16& negm, int r32, int hi) {
; #pragma unroll
;   for (int d0 = 0; d0 < 4; ++d0) { const int cb = (d0 * 16 + hi * 8) * 2;
;     const bf16x8 b0 = *reinterpret_cast<const bf16x8*>(Kr + KSWZ2(r32, cb));
;     const bf16x8 b1 = *reinterpret_cast<const bf16x8*>(Kr + KSWZ2(32 + r32, cb));
;     if (d0 == 0) { p0 = __builtin_amdgcn_mfma_f32_32x32x16_bf16(b0, qr[0], negm, 0, 0, 0); p1 = __builtin_amdgcn_mfma_f32_32x32x16_bf16(b1, qr[0], negm, 0, 0, 0); }
;     else { p0 = __builtin_amdgcn_mfma_f32_32x32x16_bf16(b0, qr[d0], p0, 0, 0, 0); p1 = __builtin_amdgcn_mfma_f32_32x32x16_bf16(b1, qr[d0], p1, 0, 0, 0); } }
; template <bool MLA> ...
;     ...
;       SWAIT(); SWRITE(bW);
;       SBAR(); qkt_pre(pB0, pB1, KR_lds + bK * SHM_KR, qr, negm, r32, hi);
;       finishSM(pA0, pA1, alA, l_reg, pa0, pa1, pa2, pa3); SBAR();
;       SLOAD((j + 2) * KVBLK); SBAR();
;       PVF(o, vb0 + bV * SHM_V, pa0, pa1, pa2, pa3); partialSM_pre<false>(pB0, pB1, Mref, negm, alB);
.LBB0_794:
	s_lshl_b32 s11, s34, 14
	s_add_i32 s11, s11, 0
	s_lshl_b32 s98, s30, 13
	v_add_u32_e32 v253, s98, v198
	ds_read_b128 v[244:247], v253 offset:53248
	ds_read_b128 v[98:101], v253 offset:49152
	s_waitcnt vmcnt(0)
	v_add_u32_e32 v252, s11, v185
	s_lshl_b32 s20, s34, 13
	s_waitcnt vmcnt(2)
	ds_write_b128 v252, v[146:149]
	v_add_u32_e32 v252, s11, v191
	s_sub_i32 s20, s11, s20
	s_mov_b32 s10, s29
	s_mov_b32 s29, s34
	s_waitcnt vmcnt(1)
	ds_write_b128 v252, v[150:153]
	v_add_u32_e32 v252, s20, v193
	s_waitcnt vmcnt(0)
	ds_write_b128 v252, v[154:157] offset:49152
	s_lshl_b32 s11, s30, 13
	s_add_i32 s11, s11, 0
	v_add_u32_e32 v150, s11, v199
	v_exp_f32_e32 v154, v90
	v_exp_f32_e32 v155, v91
	v_exp_f32_e32 v156, v92
	s_waitcnt lgkmcnt(3)
	v_mfma_f32_32x32x16_bf16 v[114:129], v[98:101], v[142:145], v[66:81]
	v_exp_f32_e32 v157, v93
	v_exp_f32_e32 v166, v94
	v_exp_f32_e32 v167, v95
	v_exp_f32_e32 v174, v96
	v_exp_f32_e32 v97, v97
	v_cvt_pk_bf16_f32 v94, v154, v155
	v_cvt_pk_bf16_f32 v95, v156, v157
	v_mfma_f32_32x32x16_bf16 v[98:113], v[244:247], v[142:145], v[66:81]
	ds_read_b128 v[146:149], v150 offset:53248
	ds_read_b128 v[150:153], v150 offset:49152
	v_cvt_pk_bf16_f32 v96, v166, v167
	s_nop 1
	v_permlane32_swap_b32_e32 v94, v96
	s_waitcnt lgkmcnt(1)
	v_mfma_f32_32x32x16_bf16 v[98:113], v[146:149], v[138:141], v[98:113]
	s_waitcnt lgkmcnt(0)
	v_mfma_f32_32x32x16_bf16 v[114:129], v[150:153], v[138:141], v[114:129]
	v_add_u32_e32 v150, s11, v200
	ds_read_b128 v[146:149], v150 offset:53248
	ds_read_b128 v[150:153], v150 offset:49152
	s_waitcnt lgkmcnt(1)
	v_mfma_f32_32x32x16_bf16 v[98:113], v[146:149], v[134:137], v[98:113]
	s_waitcnt lgkmcnt(0)
	v_mfma_f32_32x32x16_bf16 v[114:129], v[150:153], v[134:137], v[114:129]
	v_add_u32_e32 v150, s11, v201
	ds_read_b128 v[146:149], v150 offset:53248
	ds_read_b128 v[150:153], v150 offset:49152
	s_waitcnt lgkmcnt(1)
	v_mfma_f32_32x32x16_bf16 v[98:113], v[146:149], v[130:133], v[98:113]
	v_exp_f32_e32 v146, v82
	v_add_f32_e32 v82, 0, v211
	v_add_f32_e32 v82, v212, v82
	v_add_f32_e32 v82, v213, v82
	v_add_f32_e32 v82, v214, v82
	v_add_f32_e32 v82, v215, v82
	v_add_f32_e32 v82, v216, v82
	v_add_f32_e32 v82, v217, v82
	v_add_f32_e32 v82, v218, v82
	v_add_f32_e32 v82, v175, v82
	v_add_f32_e32 v82, v176, v82
	v_add_f32_e32 v82, v177, v82
	v_add_f32_e32 v82, v178, v82
	v_add_f32_e32 v82, v179, v82
	v_exp_f32_e32 v147, v83
	v_add_f32_e32 v82, v208, v82
	v_exp_f32_e32 v148, v84
	v_add_f32_e32 v82, v209, v82
	v_exp_f32_e32 v149, v85
	v_add_f32_e32 v82, v210, v82
	s_waitcnt lgkmcnt(0)
	v_mfma_f32_32x32x16_bf16 v[114:129], v[150:153], v[130:133], v[114:129]
	v_exp_f32_e32 v150, v86
	v_add_f32_e32 v82, v146, v82
	v_exp_f32_e32 v151, v87
	v_add_f32_e32 v82, v147, v82
	v_exp_f32_e32 v152, v88
	v_add_f32_e32 v82, v148, v82
	v_exp_f32_e32 v153, v89
	v_add_f32_e32 v82, v149, v82
	v_add_f32_e32 v82, v150, v82
	v_add_f32_e32 v82, v151, v82
	v_add_f32_e32 v82, v152, v82
	v_add_f32_e32 v82, v153, v82
	v_add_f32_e32 v82, v154, v82
	v_add_f32_e32 v82, v155, v82
	v_add_f32_e32 v82, v156, v82
	v_add_f32_e32 v82, v157, v82
	v_add_f32_e32 v82, v166, v82
	v_add_f32_e32 v82, v167, v82
	v_add_f32_e32 v82, v174, v82
	v_add_f32_e32 v203, v97, v82
	v_mov_b32_e32 v204, v203
	v_cvt_pk_bf16_f32 v82, v211, v212
	v_cvt_pk_bf16_f32 v84, v215, v216
	v_permlane32_swap_b32_e32 v203, v204
	v_cvt_pk_bf16_f32 v83, v213, v214
	v_cvt_pk_bf16_f32 v85, v217, v218
	v_permlane32_swap_b32_e32 v82, v84
	v_cvt_pk_bf16_f32 v86, v175, v176
	v_cvt_pk_bf16_f32 v87, v177, v178
	v_cvt_pk_bf16_f32 v88, v179, v208
	v_cvt_pk_bf16_f32 v89, v209, v210
	v_cvt_pk_bf16_f32 v90, v146, v147
	v_cvt_pk_bf16_f32 v91, v148, v149
	v_cvt_pk_bf16_f32 v92, v150, v151
	v_cvt_pk_bf16_f32 v93, v152, v153
	v_cvt_pk_bf16_f32 v97, v174, v97
	v_permlane32_swap_b32_e32 v83, v85
	v_permlane32_swap_b32_e32 v86, v88
	v_permlane32_swap_b32_e32 v87, v89
	v_permlane32_swap_b32_e32 v90, v92
	v_permlane32_swap_b32_e32 v91, v93
	v_permlane32_swap_b32_e32 v95, v97
	v_lshl_add_u64 v[178:179], s[14:15], 0, v[168:169]
	v_add_co_u32_e32 v146, vcc, s62, v178
	v_lshl_add_u64 v[176:177], s[14:15], 0, v[170:171]
	s_nop 0
	v_addc_co_u32_e32 v147, vcc, 0, v179, vcc
	v_add_co_u32_e32 v150, vcc, s62, v176
	v_lshl_add_u64 v[174:175], s[14:15], 0, v[172:173]
	s_nop 0
	v_addc_co_u32_e32 v151, vcc, 0, v177, vcc
	v_add_co_u32_e32 v154, vcc, s63, v174
	global_load_dwordx4 v[146:149], v[146:147], off
	s_nop 0
	global_load_dwordx4 v[150:153], v[150:151], off
	v_addc_co_u32_e32 v155, vcc, 0, v175, vcc
	global_load_dwordx4 v[154:157], v[154:155], off offset:2048
	v_lshl_add_u32 v166, s10, 14, v180
	ds_read_b64_tr_b16 v[206:207], v166 offset:0
	ds_read_b64_tr_b16 v[208:209], v166 offset:0x800
	ds_read_b64_tr_b16 v[210:211], v166 offset:0x1000
	ds_read_b64_tr_b16 v[212:213], v166 offset:0x1800
	ds_read_b64_tr_b16 v[214:215], v166 offset:0x2000
	ds_read_b64_tr_b16 v[216:217], v166 offset:0x2800
	ds_read_b64_tr_b16 v[218:219], v166 offset:0x3000
	ds_read_b64_tr_b16 v[220:221], v166 offset:0x3800
	s_waitcnt lgkmcnt(0)
; #define SBAR() __builtin_amdgcn_sched_barrier(0)
; #define PV_READ(S, D0) do { S##0 = tr_read<v_rd_off(D0, 0, 0)>(vb); S##1 = tr_read<v_rd_off(D0, 0, 1)>(vb); S##2 = tr_read<v_rd_off(D0, 1, 0)>(vb); S##3 = tr_read<v_rd_off(D0, 1, 1)>(vb); \
;     S##4 = tr_read<v_rd_off(D0, 2, 0)>(vb); S##5 = tr_read<v_rd_off(D0, 2, 1)>(vb); S##6 = tr_read<v_rd_off(D0, 3, 0)>(vb); S##7 = tr_read<v_rd_off(D0, 3, 1)>(vb); } while (0)
; #define PV_MMA(OD, S) do { OD = __builtin_amdgcn_mfma_f32_32x32x16_bf16(pa0, PV_PK(S##0, S##1), OD, 0, 0, 0); OD = __builtin_amdgcn_mfma_f32_32x32x16_bf16(pa1, PV_PK(S##2, S##3), OD, 0, 0, 0); \
;     OD = __builtin_amdgcn_mfma_f32_32x32x16_bf16(pa2, PV_PK(S##4, S##5), OD, 0, 0, 0); OD = __builtin_amdgcn_mfma_f32_32x32x16_bf16(pa3, PV_PK(S##6, S##7), OD, 0, 0, 0); } while (0)
; #define PV_WAIT() do { asm volatile("s_waitcnt lgkmcnt(0)" ::: "memory"); SBAR(); } while (0)
; template <bool FIRST> __device__ __forceinline__ void partialSM_pre(f32x16& p0, f32x16& p1, float& M, f32x16& negm, float& alpha) {
;   constexpr float THRL = THR * 1.4426950408889634f;
;   float pmax = p0[0];
; #pragma unroll
;   for (int r = 1; r < 16; ++r) pmax = fmaxf(pmax, p0[r]);
; #pragma unroll
;   for (int r = 0; r < 16; ++r) pmax = fmaxf(pmax, p1[r]);
;   { auto rr = __builtin_amdgcn_permlane32_swap(__float_as_uint(pmax), __float_as_uint(pmax), false, false);
;     pmax = fmaxf(__uint_as_float(rr[0]), __uint_as_float(rr[1])); }
;   if (!FIRST && __builtin_expect(__all(pmax <= THRL), 1)) { alpha = 1.f; }
; __device__ __forceinline__ void pv_pipe(f32x16* o, int vb, bf16x8 pa0, bf16x8 pa1, bf16x8 pa2, bf16x8 pa3) {
;   s16x4 a0, a1, a2, a3, a4, a5, a6, a7, b0, b1, b2, b3, b4, b5, b6, b7;
;   PV_READ(a, 0); PV_WAIT();
;   PV_READ(b, 1); SBAR(); PV_MMA(o[0], a); PV_WAIT();
;   PV_READ(a, 2); SBAR(); PV_MMA(o[1], b); PV_WAIT();
;   PV_READ(b, 3); SBAR(); PV_MMA(o[2], a); PV_WAIT();
;   PV_MMA(o[3], b);
; }
	ds_read_b64_tr_b16 v[222:223], v166 offset:0x200
	ds_read_b64_tr_b16 v[224:225], v166 offset:0xa00
	ds_read_b64_tr_b16 v[226:227], v166 offset:0x1200
	ds_read_b64_tr_b16 v[228:229], v166 offset:0x1a00
	ds_read_b64_tr_b16 v[230:231], v166 offset:0x2200
	ds_read_b64_tr_b16 v[232:233], v166 offset:0x2a00
	ds_read_b64_tr_b16 v[234:235], v166 offset:0x3200
	ds_read_b64_tr_b16 v[236:237], v166 offset:0x3a00
	s_nop 0
	v_mfma_f32_32x32x16_bf16 v[2:17], v[82:85], v[206:209], v[2:17]
	s_waitcnt lgkmcnt(0)
	v_mfma_f32_32x32x16_bf16 v[2:17], v[86:89], v[210:213], v[2:17]
	v_mfma_f32_32x32x16_bf16 v[2:17], v[90:93], v[214:217], v[2:17]
	v_mfma_f32_32x32x16_bf16 v[2:17], v[94:97], v[218:221], v[2:17]
	ds_read_b64_tr_b16 v[206:207], v166 offset:0x400
	ds_read_b64_tr_b16 v[208:209], v166 offset:0xc00
	ds_read_b64_tr_b16 v[210:211], v166 offset:0x1400
	ds_read_b64_tr_b16 v[212:213], v166 offset:0x1c00
	ds_read_b64_tr_b16 v[214:215], v166 offset:0x2400
	ds_read_b64_tr_b16 v[216:217], v166 offset:0x2c00
	ds_read_b64_tr_b16 v[218:219], v166 offset:0x3400
	ds_read_b64_tr_b16 v[220:221], v166 offset:0x3c00
	v_mfma_f32_32x32x16_bf16 v[50:65], v[82:85], v[222:225], v[50:65]
	s_waitcnt lgkmcnt(0)
	v_mfma_f32_32x32x16_bf16 v[50:65], v[86:89], v[226:229], v[50:65]
	v_mfma_f32_32x32x16_bf16 v[50:65], v[90:93], v[230:233], v[50:65]
	v_mfma_f32_32x32x16_bf16 v[50:65], v[94:97], v[234:237], v[50:65]
	ds_read_b64_tr_b16 v[222:223], v166 offset:0x600
	ds_read_b64_tr_b16 v[224:225], v166 offset:0xe00
	ds_read_b64_tr_b16 v[226:227], v166 offset:0x1600
	ds_read_b64_tr_b16 v[228:229], v166 offset:0x1e00
	ds_read_b64_tr_b16 v[230:231], v166 offset:0x2600
	ds_read_b64_tr_b16 v[232:233], v166 offset:0x2e00
	ds_read_b64_tr_b16 v[234:235], v166 offset:0x3600
	ds_read_b64_tr_b16 v[236:237], v166 offset:0x3e00
	v_mfma_f32_32x32x16_bf16 v[34:49], v[82:85], v[206:209], v[34:49]
	s_waitcnt lgkmcnt(0)
	v_mfma_f32_32x32x16_bf16 v[34:49], v[86:89], v[210:213], v[34:49]
	v_mfma_f32_32x32x16_bf16 v[34:49], v[90:93], v[214:217], v[34:49]
	v_mfma_f32_32x32x16_bf16 v[34:49], v[94:97], v[218:221], v[34:49]
	v_mfma_f32_32x32x16_bf16 v[18:33], v[82:85], v[222:225], v[18:33]
	v_max_f32_e32 v82, v115, v115
	v_max_f32_e32 v83, v114, v114
	v_max_f32_e32 v82, v83, v82
	v_max3_f32 v82, v82, v116, v117
	v_max3_f32 v82, v82, v118, v119
	v_max3_f32 v82, v82, v120, v121
	v_max3_f32 v82, v82, v122, v123
	v_mfma_f32_32x32x16_bf16 v[18:33], v[86:89], v[226:229], v[18:33]
	v_max3_f32 v82, v82, v124, v125
	v_max3_f32 v82, v82, v126, v127
	v_max3_f32 v82, v82, v128, v129
	v_max3_f32 v82, v82, v98, v99
	v_max3_f32 v82, v82, v100, v101
	v_max3_f32 v82, v82, v102, v103
	v_max3_f32 v82, v82, v104, v105
	v_mfma_f32_32x32x16_bf16 v[18:33], v[90:93], v[230:233], v[18:33]
	v_max3_f32 v82, v82, v106, v107
	v_max3_f32 v82, v82, v108, v109
	v_max3_f32 v82, v82, v110, v111
	v_max3_f32 v82, v82, v112, v113
	v_mov_b32_e32 v83, v82
	s_nop 1
	v_permlane32_swap_b32_e32 v82, v83
	v_mfma_f32_32x32x16_bf16 v[18:33], v[94:97], v[234:237], v[18:33]
	v_max_f32_e32 v83, v83, v83
	v_max_f32_e32 v82, v82, v82
	v_max_f32_e32 v82, v82, v83
	v_cmp_ge_f32_e32 vcc, s12, v82
	s_cmp_eq_u64 vcc, exec
	s_cbranch_scc0 .LBB0_808
	v_mov_b32_e32 v205, 1.0
	v_cmp_gt_f32_e32 vcc, 1.0, v205
	s_cbranch_vccz .LBB0_799

; #define SBAR() __builtin_amdgcn_sched_barrier(0)
; #define SWRITE(b) do { *(bf16x8*)(V_lds + (b) * SHM_V + vst0) = vs0; *(bf16x8*)(V_lds + (b) * SHM_V + vst1) = vs1; \
;     if constexpr (MLA) { *(bf16x8*)(KN_lds + (b) * SHM_KN + KSWZ(sr, sc * 2)) = kn0; *(bf16x8*)(KN_lds + (b) * SHM_KN + KSWZ(32 + sr, sc * 2)) = kn1; } \
;     *(bf16x8*)(KR_lds + (b) * SHM_KR + KSWZ2(kr_r, kr_c * 2)) = kr0; } while (0)
; #define SWAIT() asm volatile("s_waitcnt vmcnt(0)" ::: "memory")
; __device__ __forceinline__ void qkt_pre(f32x16& p0, f32x16& p1, const char* Kr, const bf16x8* qr, const f32x16& negm, int r32, int hi) {
; #pragma unroll
;   for (int d0 = 0; d0 < 4; ++d0) { const int cb = (d0 * 16 + hi * 8) * 2;
;     const bf16x8 b0 = *reinterpret_cast<const bf16x8*>(Kr + KSWZ2(r32, cb));
;     const bf16x8 b1 = *reinterpret_cast<const bf16x8*>(Kr + KSWZ2(32 + r32, cb));
;     if (d0 == 0) { p0 = __builtin_amdgcn_mfma_f32_32x32x16_bf16(b0, qr[0], negm, 0, 0, 0); p1 = __builtin_amdgcn_mfma_f32_32x32x16_bf16(b1, qr[0], negm, 0, 0, 0); }
;     else { p0 = __builtin_amdgcn_mfma_f32_32x32x16_bf16(b0, qr[d0], p0, 0, 0, 0); p1 = __builtin_amdgcn_mfma_f32_32x32x16_bf16(b1, qr[d0], p1, 0, 0, 0); } }
; template <bool MLA> ...
;     ...
;       SWAIT(); SWRITE(bW);
;       SBAR(); qkt_pre(pA0, pA1, KR_lds + bK * SHM_KR, qr, negm, r32, hi);
;       finishSM(pB0, pB1, alB, l_reg, pa0, pa1, pa2, pa3); SBAR();
;       if (j + 3 < NT) SLOAD((j + 3) * KVBLK); SBAR();
.LBB0_799:
	s_add_i32 s10, s29, 1
	s_cmp_lg_u32 s29, 2
	s_cselect_b32 s31, s10, 0
	s_lshl_b32 s10, s31, 14
	s_add_i32 s10, s10, 0
	s_barrier
	v_add_u32_e32 v253, s20, v198
	ds_read_b128 v[206:209], v253 offset:53248
	ds_read_b128 v[82:85], v253 offset:49152
	s_waitcnt vmcnt(0)
	v_add_u32_e32 v252, s10, v185
	s_waitcnt vmcnt(2)
	ds_write_b128 v252, v[146:149]
	v_add_u32_e32 v252, s10, v191
	s_waitcnt vmcnt(1)
	ds_write_b128 v252, v[150:153]
	v_lshl_add_u32 v252, s31, 13, v194
	v_exp_f32_e32 v166, v114
	v_exp_f32_e32 v167, v115
	v_exp_f32_e32 v214, v116
	v_exp_f32_e32 v215, v117
	v_exp_f32_e32 v216, v118
	v_exp_f32_e32 v217, v119
	v_exp_f32_e32 v218, v120
	v_exp_f32_e32 v219, v121
	v_exp_f32_e32 v220, v122
	v_exp_f32_e32 v221, v123
	v_exp_f32_e32 v222, v124
	v_exp_f32_e32 v223, v125
	v_exp_f32_e32 v224, v126
	v_exp_f32_e32 v225, v127
	v_exp_f32_e32 v226, v128
	v_exp_f32_e32 v227, v129
	s_waitcnt vmcnt(0)
	ds_write_b128 v252, v[154:157] offset:49152
	v_add_u32_e32 v210, s20, v199
	v_exp_f32_e32 v228, v104
	v_exp_f32_e32 v229, v105
	v_exp_f32_e32 v230, v106
	s_waitcnt lgkmcnt(3)
	v_mfma_f32_32x32x16_bf16 v[114:129], v[82:85], v[142:145], v[66:81]
	v_exp_f32_e32 v231, v107
	v_exp_f32_e32 v232, v108
	v_exp_f32_e32 v233, v109
	v_exp_f32_e32 v234, v110
	v_exp_f32_e32 v235, v111
	v_exp_f32_e32 v236, v112
	v_exp_f32_e32 v113, v113
	v_mfma_f32_32x32x16_bf16 v[82:97], v[206:209], v[142:145], v[66:81]
	ds_read_b128 v[206:209], v210 offset:53248
	ds_read_b128 v[210:213], v210 offset:49152
	v_cvt_pk_bf16_f32 v104, v224, v225
	v_cvt_pk_bf16_f32 v105, v226, v227
	v_cvt_pk_bf16_f32 v109, v228, v229
	v_cvt_pk_bf16_f32 v110, v230, v231
	v_cvt_pk_bf16_f32 v111, v232, v233
	v_cvt_pk_bf16_f32 v112, v234, v235
	s_waitcnt lgkmcnt(1)
	v_mfma_f32_32x32x16_bf16 v[82:97], v[206:209], v[138:141], v[82:97]
	v_permlane32_swap_b32_e32 v110, v112
	s_waitcnt lgkmcnt(0)
	v_mfma_f32_32x32x16_bf16 v[114:129], v[210:213], v[138:141], v[114:129]
	v_add_u32_e32 v210, s20, v200
	ds_read_b128 v[206:209], v210 offset:53248
	ds_read_b128 v[210:213], v210 offset:49152
	s_waitcnt lgkmcnt(1)
	v_mfma_f32_32x32x16_bf16 v[82:97], v[206:209], v[134:137], v[82:97]
	s_waitcnt lgkmcnt(0)
	v_mfma_f32_32x32x16_bf16 v[114:129], v[210:213], v[134:137], v[114:129]
	v_add_u32_e32 v210, s20, v201
	ds_read_b128 v[206:209], v210 offset:53248
	ds_read_b128 v[210:213], v210 offset:49152
	s_waitcnt lgkmcnt(1)
	v_mfma_f32_32x32x16_bf16 v[82:97], v[206:209], v[130:133], v[82:97]
	v_exp_f32_e32 v208, v98
	v_add_f32_e32 v98, 0, v166
	v_add_f32_e32 v98, v167, v98
	v_add_f32_e32 v98, v214, v98
	v_add_f32_e32 v98, v215, v98
	v_add_f32_e32 v98, v216, v98
	v_add_f32_e32 v98, v217, v98
	v_add_f32_e32 v98, v218, v98
	v_add_f32_e32 v98, v219, v98
	v_add_f32_e32 v98, v220, v98
	v_add_f32_e32 v98, v221, v98
	v_add_f32_e32 v98, v222, v98
	v_add_f32_e32 v98, v223, v98
	v_add_f32_e32 v98, v224, v98
	v_exp_f32_e32 v209, v99
	v_add_f32_e32 v98, v225, v98
	s_waitcnt lgkmcnt(0)
	v_mfma_f32_32x32x16_bf16 v[114:129], v[210:213], v[130:133], v[114:129]
	v_exp_f32_e32 v210, v100
	v_add_f32_e32 v98, v226, v98
	v_exp_f32_e32 v211, v101
	v_add_f32_e32 v98, v227, v98
	v_exp_f32_e32 v212, v102
	v_add_f32_e32 v98, v208, v98
	v_exp_f32_e32 v213, v103
	v_add_f32_e32 v98, v209, v98
	v_add_f32_e32 v98, v210, v98
	v_add_f32_e32 v98, v211, v98
	v_add_f32_e32 v98, v212, v98
	v_add_f32_e32 v98, v213, v98
	v_add_f32_e32 v98, v228, v98
	v_add_f32_e32 v98, v229, v98
	v_add_f32_e32 v98, v230, v98
	v_add_f32_e32 v98, v231, v98
	v_add_f32_e32 v98, v232, v98
	v_add_f32_e32 v98, v233, v98
	v_add_f32_e32 v98, v234, v98
	v_add_f32_e32 v98, v235, v98
	v_add_f32_e32 v98, v236, v98
	v_add_f32_e32 v206, v113, v98
	v_mov_b32_e32 v207, v206
	v_cvt_pk_bf16_f32 v98, v166, v167
	v_cvt_pk_bf16_f32 v99, v214, v215
	v_cvt_pk_bf16_f32 v100, v216, v217
	v_cvt_pk_bf16_f32 v101, v218, v219
	v_cvt_pk_bf16_f32 v102, v220, v221
	v_cvt_pk_bf16_f32 v103, v222, v223
	v_cvt_pk_bf16_f32 v106, v208, v209
	v_cvt_pk_bf16_f32 v107, v210, v211
	v_cvt_pk_bf16_f32 v108, v212, v213
	v_cvt_pk_bf16_f32 v113, v236, v113
	v_permlane32_swap_b32_e32 v206, v207
	v_permlane32_swap_b32_e32 v98, v100
	v_permlane32_swap_b32_e32 v99, v101
	v_permlane32_swap_b32_e32 v102, v104
	v_permlane32_swap_b32_e32 v103, v105
	v_permlane32_swap_b32_e32 v106, v108
	v_permlane32_swap_b32_e32 v107, v109
	v_permlane32_swap_b32_e32 v111, v113
	s_cmp_gt_u32 s28, 60
	s_cselect_b64 s[20:21], -1, 0
	s_and_b64 vcc, exec, s[20:21]
	s_cbranch_vccnz .LBB0_801
	v_add_co_u32_e32 v146, vcc, 0x19f81000, v178
	s_nop 1
	v_addc_co_u32_e32 v147, vcc, 0, v179, vcc
	v_add_co_u32_e32 v150, vcc, 0x19f81000, v176
	s_nop 1
	v_addc_co_u32_e32 v151, vcc, 0, v177, vcc
	v_add_co_u32_e32 v154, vcc, 0x19f80000, v174
	global_load_dwordx4 v[146:149], v[146:147], off
	s_nop 0
	global_load_dwordx4 v[150:153], v[150:151], off
	v_addc_co_u32_e32 v155, vcc, 0, v175, vcc
	global_load_dwordx4 v[154:157], v[154:155], off offset:2048
